# one barrier per GEMM super-phase (per-half loop copies) + FNORM loop no longer waits for its own store acks + mLSTM-out unit keeps its state-fragment loads in flight across the tile staging + 64-bit a
# baseline (speedup 1.0000x reference)
; #define PG8_LAS __attribute__((address_space(3)))
;     __device__ __forceinline__ void stage(const Unit& u, PG8_LAS unsigned char* area, int wr, int lane) const {
;         const float* src = rs + u.pm * BM + wr * 64 + lane;
;         __builtin_amdgcn_global_load_lds((const unsigned*)src, (PG8_LAS unsigned*)area, 4, 0, 0);
;         __builtin_amdgcn_global_load_lds((const unsigned*)(src + HALF), (PG8_LAS unsigned*)(area + 256), 4, 0, 0);
;     }
; template <class Epi, class Sched, bool ALIGN_EPI = false, bool SP2 = false, bool ABLK = false, bool BBLK = false>
; __device__ __forceinline__ void gemm_phase(PG8_LAS unsigned char* lds, const Gemm g, const Sched& S, const Epi& E) {
;     ...
; #pragma unroll
;         for (int a = 0; a < 2; ++a)
; #pragma unroll
;             for (int b = 0; b < 2; ++b)
; #pragma unroll
;                 for (int m = 0; m < 4; ++m)
; #pragma unroll
;                     for (int n = 0; n < 2; ++n) acc[a][b][m][n] = (f32x4){0.f, 0.f, 0.f, 0.f};
;         cur = nxt; cA = nA; cB = nB; ++ui;
.LBB0_184:
	s_lshl_b32 s10, s18, 8
	s_ashr_i32 s11, s10, 31
	s_mov_b32 m0, s64
	v_lshl_add_u64 v[4:5], s[10:11], 2, v[144:145]
	global_load_lds_dword v[4:5], off
	v_lshl_add_u64 v[4:5], v[4:5], 0, s[90:91]
	s_add_i32 m0, s64, 0x100
	s_ashr_i32 s9, s8, 31
	global_load_lds_dword v[4:5], off
	s_lshl_b64 s[10:11], s[8:9], 20
	v_readlane_b32 s16, v252, 27
	v_readlane_b32 s17, v252, 28
	s_add_u32 s10, s16, s10
	s_addc_u32 s11, s17, s11
	s_and_b64 s[16:17], s[2:3], exec
	s_cselect_b32 s9, s11, s21
	s_cselect_b32 s70, s10, s20
	s_ashr_i32 s7, s6, 31
	s_lshl_b64 s[16:17], s[6:7], 20
	s_add_u32 s16, s29, s16
	s_addc_u32 s17, s30, s17
	s_and_b64 s[24:25], s[2:3], exec
	s_cselect_b32 s7, s17, s23
	s_cselect_b32 s71, s16, s22
	s_add_u32 s20, s20, 0xc000
	s_addc_u32 s21, s21, 0
	s_add_u32 s77, s22, 0x10000
	v_mov_b32_e32 v4, 0
	s_addc_u32 vcc_lo, s23, 0
	s_mov_b32 vcc_hi, -2
	v_mov_b32_e32 v5, v4
	v_mov_b64_e32 v[6:7], 0
	v_mov_b64_e32 v[8:9], 0
	v_mov_b64_e32 v[10:11], 0
	v_mov_b64_e32 v[20:21], 0
	v_mov_b64_e32 v[22:23], 0
	v_mov_b64_e32 v[24:25], 0
	v_mov_b64_e32 v[26:27], 0
	v_mov_b64_e32 v[40:41], 0
	v_mov_b64_e32 v[42:43], 0
	v_mov_b64_e32 v[44:45], 0
	v_mov_b64_e32 v[46:47], 0
	v_mov_b64_e32 v[56:57], 0
	v_mov_b64_e32 v[58:59], 0
	v_mov_b64_e32 v[60:61], 0
	v_mov_b64_e32 v[62:63], 0
	v_mov_b64_e32 v[12:13], 0
	v_mov_b64_e32 v[14:15], 0
	v_mov_b64_e32 v[16:17], 0
	v_mov_b64_e32 v[18:19], 0
	v_mov_b64_e32 v[28:29], 0
	v_mov_b64_e32 v[30:31], 0
	v_mov_b64_e32 v[32:33], 0
	v_mov_b64_e32 v[34:35], 0
	v_mov_b64_e32 v[48:49], 0
	v_mov_b64_e32 v[50:51], 0
	v_mov_b64_e32 v[52:53], 0
	v_mov_b64_e32 v[54:55], 0
	v_mov_b64_e32 v[64:65], 0
	v_mov_b64_e32 v[66:67], 0
	v_mov_b64_e32 v[68:69], 0
	v_mov_b64_e32 v[70:71], 0
	v_mov_b64_e32 v[72:73], 0
	v_mov_b64_e32 v[74:75], 0
	v_mov_b64_e32 v[76:77], 0
	v_mov_b64_e32 v[78:79], 0
	v_mov_b64_e32 v[88:89], 0
	v_mov_b64_e32 v[90:91], 0
	v_mov_b64_e32 v[92:93], 0
	v_mov_b64_e32 v[94:95], 0
	v_mov_b64_e32 v[104:105], 0
	v_mov_b64_e32 v[106:107], 0
	v_mov_b64_e32 v[108:109], 0
	v_mov_b64_e32 v[110:111], 0
	v_mov_b64_e32 v[120:121], 0
	v_mov_b64_e32 v[122:123], 0
	v_mov_b64_e32 v[124:125], 0
	v_mov_b64_e32 v[126:127], 0
	v_mov_b64_e32 v[80:81], 0
	v_mov_b64_e32 v[82:83], 0
	v_mov_b64_e32 v[84:85], 0
	v_mov_b64_e32 v[86:87], 0
	v_mov_b64_e32 v[96:97], 0
	v_mov_b64_e32 v[98:99], 0
	v_mov_b64_e32 v[100:101], 0
	v_mov_b64_e32 v[102:103], 0
	v_mov_b64_e32 v[112:113], 0
	v_mov_b64_e32 v[114:115], 0
	v_mov_b64_e32 v[116:117], 0
	v_mov_b64_e32 v[118:119], 0
	v_mov_b64_e32 v[128:129], 0
	v_mov_b64_e32 v[130:131], 0
	v_mov_b64_e32 v[132:133], 0
	v_mov_b64_e32 v[134:135], 0
	s_cmp_eq_u32 s100, 0
	s_cbranch_scc0 .Lk1_FFN1

; template <class Epi, class Sched, bool ALIGN_EPI = false, bool SP2 = false, bool ABLK = false, bool BBLK = false>
; __device__ __forceinline__ void gemm_phase(PG8_LAS unsigned char* lds, const Gemm g, const Sched& S, const Epi& E) {
;     ...
; #pragma unroll
;         for (int a = 0; a < 2; ++a)
; #pragma unroll
;             for (int b = 0; b < 2; ++b)
; #pragma unroll
;                 for (int m = 0; m < 4; ++m)
; #pragma unroll
;                     for (int n = 0; n < 2; ++n) acc[a][b][m][n] = (f32x4){0.f, 0.f, 0.f, 0.f};
;         cur = nxt; cA = nA; cB = nB; ++ui;
.LBB0_438:
	s_add_u32 s10, s10, 0xc000
	s_addc_u32 s11, s11, 0
	s_add_u32 vcc_lo, s16, 0x10000
	v_mov_b32_e32 v4, 0
	s_addc_u32 vcc_hi, s17, 0
	s_mov_b32 s13, -2
	v_mov_b32_e32 v5, v4
	v_mov_b64_e32 v[6:7], 0
	v_mov_b64_e32 v[8:9], 0
	v_mov_b64_e32 v[10:11], 0
	v_mov_b64_e32 v[12:13], 0
	v_mov_b64_e32 v[14:15], 0
	v_mov_b64_e32 v[16:17], 0
	v_mov_b64_e32 v[18:19], 0
	v_mov_b64_e32 v[28:29], 0
	v_mov_b64_e32 v[30:31], 0
	v_mov_b64_e32 v[32:33], 0
	v_mov_b64_e32 v[34:35], 0
	v_mov_b64_e32 v[48:49], 0
	v_mov_b64_e32 v[50:51], 0
	v_mov_b64_e32 v[52:53], 0
	v_mov_b64_e32 v[54:55], 0
	v_mov_b64_e32 v[20:21], 0
	v_mov_b64_e32 v[22:23], 0
	v_mov_b64_e32 v[24:25], 0
	v_mov_b64_e32 v[26:27], 0
	v_mov_b64_e32 v[40:41], 0
	v_mov_b64_e32 v[42:43], 0
	v_mov_b64_e32 v[44:45], 0
	v_mov_b64_e32 v[46:47], 0
	v_mov_b64_e32 v[56:57], 0
	v_mov_b64_e32 v[58:59], 0
	v_mov_b64_e32 v[60:61], 0
	v_mov_b64_e32 v[62:63], 0
	v_mov_b64_e32 v[64:65], 0
	v_mov_b64_e32 v[66:67], 0
	v_mov_b64_e32 v[68:69], 0
	v_mov_b64_e32 v[70:71], 0
	v_mov_b64_e32 v[72:73], 0
	v_mov_b64_e32 v[74:75], 0
	v_mov_b64_e32 v[76:77], 0
	v_mov_b64_e32 v[78:79], 0
	v_mov_b64_e32 v[80:81], 0
	v_mov_b64_e32 v[82:83], 0
	v_mov_b64_e32 v[84:85], 0
	v_mov_b64_e32 v[86:87], 0
	v_mov_b64_e32 v[96:97], 0
	v_mov_b64_e32 v[98:99], 0
	v_mov_b64_e32 v[100:101], 0
	v_mov_b64_e32 v[102:103], 0
	v_mov_b64_e32 v[112:113], 0
	v_mov_b64_e32 v[114:115], 0
	v_mov_b64_e32 v[116:117], 0
	v_mov_b64_e32 v[118:119], 0
	v_mov_b64_e32 v[88:89], 0
	v_mov_b64_e32 v[90:91], 0
	v_mov_b64_e32 v[92:93], 0
	v_mov_b64_e32 v[94:95], 0
	v_mov_b64_e32 v[104:105], 0
	v_mov_b64_e32 v[106:107], 0
	v_mov_b64_e32 v[108:109], 0
	v_mov_b64_e32 v[110:111], 0
	v_mov_b64_e32 v[120:121], 0
	v_mov_b64_e32 v[122:123], 0
	v_mov_b64_e32 v[124:125], 0
	v_mov_b64_e32 v[126:127], 0
	v_mov_b64_e32 v[128:129], 0
	v_mov_b64_e32 v[130:131], 0
	v_mov_b64_e32 v[132:133], 0
	v_mov_b64_e32 v[134:135], 0
	s_cmp_eq_u32 s100, 0
	s_cbranch_scc0 .Lk1_FFN2

; #define PG8_LAS __attribute__((address_space(3)))
;     __device__ __forceinline__ void stage(const Unit& u, PG8_LAS unsigned char* area, int wr, int lane) const {
;         if (rs) { const float* src = rs + u.pm * BM + wr * 64 + lane;
;             __builtin_amdgcn_global_load_lds((const unsigned*)src, (PG8_LAS unsigned*)area, 4, 0, 0);
;             __builtin_amdgcn_global_load_lds((const unsigned*)(src + HALF), (PG8_LAS unsigned*)(area + 256), 4, 0, 0); }
;     }
; template <class Epi, class Sched, bool ALIGN_EPI = false, bool SP2 = false, bool ABLK = false, bool BBLK = false>
; __device__ __forceinline__ void gemm_phase(PG8_LAS unsigned char* lds, const Gemm g, const Sched& S, const Epi& E) {
;     ...
; #pragma unroll
;         for (int a = 0; a < 2; ++a)
; #pragma unroll
;             for (int b = 0; b < 2; ++b)
; #pragma unroll
;                 for (int m = 0; m < 4; ++m)
; #pragma unroll
;                     for (int n = 0; n < 2; ++n) acc[a][b][m][n] = (f32x4){0.f, 0.f, 0.f, 0.f};
;         cur = nxt; cA = nA; cB = nB; ++ui;
.LBB0_915:
	s_lshl_b32 s18, s0, 8
	s_ashr_i32 s19, s18, 31
	s_mov_b32 m0, s63
	v_lshl_add_u64 v[4:5], s[18:19], 2, v[144:145]
	v_lshl_add_u64 v[6:7], v[4:5], 0, s[90:91]
	global_load_lds_dword v[4:5], off
	s_add_i32 m0, s63, 0x100
	s_mov_b32 s0, s1
	global_load_lds_dword v[6:7], off
	s_ashr_i32 s1, s1, 31
	s_lshl_b64 s[10:11], s[0:1], 20
	v_readlane_b32 s16, v252, 27
	v_readlane_b32 s17, v252, 28
	s_add_u32 s10, s16, s10
	s_addc_u32 s11, s17, s11
	s_and_b64 s[16:17], s[2:3], exec
	s_cselect_b32 s1, s11, s21
	s_cselect_b32 s19, s10, s20
	s_ashr_i32 s9, s8, 31
	s_lshl_b64 s[16:17], s[8:9], 20
	v_readlane_b32 s24, v254, 5
	v_readlane_b32 s25, v254, 6
	s_add_u32 s16, s24, s16
	s_addc_u32 s17, s25, s17
	s_and_b64 s[24:25], s[2:3], exec
	s_cselect_b32 s9, s17, s23
	s_cselect_b32 s65, s16, s22
	s_add_u32 s20, s20, 0xc000
	s_addc_u32 s21, s21, 0
	s_add_u32 s70, s22, 0x10000
	v_mov_b32_e32 v4, 0
	s_addc_u32 s71, s23, 0
	s_mov_b32 s13, -2
	v_mov_b32_e32 v5, v4
	v_mov_b64_e32 v[6:7], 0
	v_mov_b64_e32 v[8:9], 0
	v_mov_b64_e32 v[10:11], 0
	v_mov_b64_e32 v[12:13], 0
	v_mov_b64_e32 v[14:15], 0
	v_mov_b64_e32 v[20:21], 0
	v_mov_b64_e32 v[22:23], 0
	v_mov_b64_e32 v[28:29], 0
	v_mov_b64_e32 v[30:31], 0
	v_mov_b64_e32 v[40:41], 0
	v_mov_b64_e32 v[42:43], 0
	v_mov_b64_e32 v[48:49], 0
	v_mov_b64_e32 v[50:51], 0
	v_mov_b64_e32 v[56:57], 0
	v_mov_b64_e32 v[58:59], 0
	v_mov_b64_e32 v[16:17], 0
	v_mov_b64_e32 v[18:19], 0
	v_mov_b64_e32 v[24:25], 0
	v_mov_b64_e32 v[26:27], 0
	v_mov_b64_e32 v[32:33], 0
	v_mov_b64_e32 v[34:35], 0
	v_mov_b64_e32 v[44:45], 0
	v_mov_b64_e32 v[46:47], 0
	v_mov_b64_e32 v[52:53], 0
	v_mov_b64_e32 v[54:55], 0
	v_mov_b64_e32 v[60:61], 0
	v_mov_b64_e32 v[62:63], 0
	v_mov_b64_e32 v[64:65], 0
	v_mov_b64_e32 v[66:67], 0
	v_mov_b64_e32 v[68:69], 0
	v_mov_b64_e32 v[70:71], 0
	v_mov_b64_e32 v[72:73], 0
	v_mov_b64_e32 v[74:75], 0
	v_mov_b64_e32 v[76:77], 0
	v_mov_b64_e32 v[78:79], 0
	v_mov_b64_e32 v[80:81], 0
	v_mov_b64_e32 v[82:83], 0
	v_mov_b64_e32 v[88:89], 0
	v_mov_b64_e32 v[90:91], 0
	v_mov_b64_e32 v[96:97], 0
	v_mov_b64_e32 v[98:99], 0
	v_mov_b64_e32 v[104:105], 0
	v_mov_b64_e32 v[106:107], 0
	v_mov_b64_e32 v[112:113], 0
	v_mov_b64_e32 v[114:115], 0
	v_mov_b64_e32 v[120:121], 0
	v_mov_b64_e32 v[122:123], 0
	v_mov_b64_e32 v[84:85], 0
	v_mov_b64_e32 v[86:87], 0
	v_mov_b64_e32 v[92:93], 0
	v_mov_b64_e32 v[94:95], 0
	v_mov_b64_e32 v[100:101], 0
	v_mov_b64_e32 v[102:103], 0
	v_mov_b64_e32 v[108:109], 0
	v_mov_b64_e32 v[110:111], 0
	v_mov_b64_e32 v[116:117], 0
	v_mov_b64_e32 v[118:119], 0
	v_mov_b64_e32 v[124:125], 0
	v_mov_b64_e32 v[126:127], 0
	v_mov_b64_e32 v[128:129], 0
	v_mov_b64_e32 v[130:131], 0
	v_mov_b64_e32 v[132:133], 0
	v_mov_b64_e32 v[134:135], 0
	s_cmp_eq_u32 s100, 0
	s_cbranch_scc0 .Lk1_MIN

; template <class Epi, class Sched, bool ALIGN_EPI = false, bool SP2 = false, bool ABLK = false, bool BBLK = false>
; __device__ __forceinline__ void gemm_phase(PG8_LAS unsigned char* lds, const Gemm g, const Sched& S, const Epi& E) {
;     ...
; #pragma unroll
;         for (int a = 0; a < 2; ++a)
; #pragma unroll
;             for (int b = 0; b < 2; ++b)
; #pragma unroll
;                 for (int m = 0; m < 4; ++m)
; #pragma unroll
;                     for (int n = 0; n < 2; ++n) acc[a][b][m][n] = (f32x4){0.f, 0.f, 0.f, 0.f};
;         cur = nxt; cA = nA; cB = nB; ++ui;
.LBB0_2110:
	s_ashr_i32 s17, s16, 31
	s_lshl_b64 s[12:13], s[16:17], 20
	s_add_u32 s18, s72, s12
	s_addc_u32 s19, s73, s13
	s_and_b64 s[12:13], s[4:5], exec
	s_cselect_b32 s12, s19, s23
	s_cselect_b32 s17, s18, s22
	s_ashr_i32 s11, s10, 31
	s_lshl_b64 s[20:21], s[10:11], 20
	v_readlane_b32 s26, v254, 3
	v_readlane_b32 s27, v254, 4
	s_add_u32 s20, s26, s20
	s_addc_u32 s21, s27, s21
	s_and_b64 s[26:27], s[4:5], exec
	s_cselect_b32 s11, s21, s25
	s_cselect_b32 s77, s20, s24
	s_add_u32 s22, s22, 0xc000
	s_addc_u32 s23, s23, 0
	s_add_u32 s82, s24, 0x10000
	v_mov_b32_e32 v4, 0
	s_addc_u32 vcc_lo, s25, 0
	s_mov_b32 s13, -2
	v_mov_b32_e32 v5, v4
	v_mov_b64_e32 v[6:7], 0
	v_mov_b64_e32 v[8:9], 0
	v_mov_b64_e32 v[10:11], 0
	v_mov_b64_e32 v[12:13], 0
	v_mov_b64_e32 v[14:15], 0
	v_mov_b64_e32 v[16:17], 0
	v_mov_b64_e32 v[18:19], 0
	v_mov_b64_e32 v[28:29], 0
	v_mov_b64_e32 v[30:31], 0
	v_mov_b64_e32 v[32:33], 0
	v_mov_b64_e32 v[34:35], 0
	v_mov_b64_e32 v[48:49], 0
	v_mov_b64_e32 v[50:51], 0
	v_mov_b64_e32 v[52:53], 0
	v_mov_b64_e32 v[54:55], 0
	v_mov_b64_e32 v[20:21], 0
	v_mov_b64_e32 v[22:23], 0
	v_mov_b64_e32 v[24:25], 0
	v_mov_b64_e32 v[26:27], 0
	v_mov_b64_e32 v[40:41], 0
	v_mov_b64_e32 v[42:43], 0
	v_mov_b64_e32 v[44:45], 0
	v_mov_b64_e32 v[46:47], 0
	v_mov_b64_e32 v[56:57], 0
	v_mov_b64_e32 v[58:59], 0
	v_mov_b64_e32 v[60:61], 0
	v_mov_b64_e32 v[62:63], 0
	v_mov_b64_e32 v[64:65], 0
	v_mov_b64_e32 v[66:67], 0
	v_mov_b64_e32 v[68:69], 0
	v_mov_b64_e32 v[70:71], 0
	v_mov_b64_e32 v[72:73], 0
	v_mov_b64_e32 v[74:75], 0
	v_mov_b64_e32 v[76:77], 0
	v_mov_b64_e32 v[78:79], 0
	v_mov_b64_e32 v[80:81], 0
	v_mov_b64_e32 v[82:83], 0
	v_mov_b64_e32 v[84:85], 0
	v_mov_b64_e32 v[86:87], 0
	v_mov_b64_e32 v[96:97], 0
	v_mov_b64_e32 v[98:99], 0
	v_mov_b64_e32 v[100:101], 0
	v_mov_b64_e32 v[102:103], 0
	v_mov_b64_e32 v[112:113], 0
	v_mov_b64_e32 v[114:115], 0
	v_mov_b64_e32 v[116:117], 0
	v_mov_b64_e32 v[118:119], 0
	v_mov_b64_e32 v[88:89], 0
	v_mov_b64_e32 v[90:91], 0
	v_mov_b64_e32 v[92:93], 0
	v_mov_b64_e32 v[94:95], 0
	v_mov_b64_e32 v[104:105], 0
	v_mov_b64_e32 v[106:107], 0
	v_mov_b64_e32 v[108:109], 0
	v_mov_b64_e32 v[110:111], 0
	v_mov_b64_e32 v[120:121], 0
	v_mov_b64_e32 v[122:123], 0
	v_mov_b64_e32 v[124:125], 0
	v_mov_b64_e32 v[126:127], 0
	v_mov_b64_e32 v[128:129], 0
	v_mov_b64_e32 v[130:131], 0
	v_mov_b64_e32 v[132:133], 0
	v_mov_b64_e32 v[134:135], 0
	s_cmp_eq_u32 s100, 0
	s_cbranch_scc0 .Lk1_MOUT
